# accumulator zeroing in front of every GEMM unit with 64 v_mov_b64 instead of 128 v_mov_b32
# baseline (speedup 1.0000x reference)
; template <class Epi, class Sched, bool ALIGN_EPI = false, bool SP2 = false>
; __device__ __forceinline__ void gemm_phase(PG8_LAS unsigned char* lds, const Gemm g, const Sched& S, const Epi& E) {
;     ...
;         const bool has_next = S.next(ui + 1, nxt);
;         const char* nA = has_next ? (const char*)g.A + (size_t)nxt.pm * tstep : cA; const char* nB = has_next ? (const char*)g.Bt + (size_t)nxt.pn * tstep : cB;
;         for (int t = 0; t < nt; t += 2) {
;             const bool last = (t == nt - 2);
;             const char* a1 = cA + (size_t)(t + 1) * kstep;
;             const char* a2 = last ? nA : cA + (size_t)(t + 2) * kstep; const char* b2 = last ? nB : cB + (size_t)(t + 2) * kstep;
;             const char* a3 = a2 + kstep; const char* b3 = b2 + kstep;
;     ...
; #pragma unroll
;         for (int a = 0; a < 2; ++a)
; #pragma unroll
;             for (int b = 0; b < 2; ++b)
; #pragma unroll
;                 for (int m = 0; m < 4; ++m)
; #pragma unroll
;                     for (int n = 0; n < 2; ++n) acc[a][b][m][n] = (f32x4){0.f, 0.f, 0.f, 0.f};
;         cur = nxt; cA = nA; cB = nB; ++ui;
.LBB0_285:
	s_ashr_i32 s21, s20, 31
	s_lshl_b64 s[22:23], s[20:21], 19
	s_add_u32 s22, s15, s22
	s_addc_u32 s23, s28, s23
	s_and_b64 s[24:25], s[12:13], exec
	s_cselect_b32 s21, s23, s27
	s_cselect_b32 s52, s22, s26
	s_ashr_i32 s17, s16, 31
	s_lshl_b64 s[24:25], s[16:17], 19
	s_add_u32 s24, s10, s24
	s_addc_u32 s25, s11, s25
	s_and_b64 s[40:41], s[12:13], exec
	s_cselect_b32 s17, s25, s39
	s_cselect_b32 s53, s24, s38
	s_add_u32 s26, s26, 0x40080
	s_addc_u32 s27, s27, 0
	s_add_u32 s54, s38, 0x100
	v_mov_b64_e32 v[2:3], 0
	v_mov_b64_e32 v[4:5], 0
	v_mov_b64_e32 v[6:7], 0
	v_mov_b64_e32 v[8:9], 0
	v_mov_b64_e32 v[10:11], 0
	v_mov_b64_e32 v[12:13], 0
	v_mov_b64_e32 v[14:15], 0
	v_mov_b64_e32 v[16:17], 0
	v_mov_b64_e32 v[18:19], 0
	v_mov_b64_e32 v[20:21], 0
	v_mov_b64_e32 v[22:23], 0
	v_mov_b64_e32 v[24:25], 0
	v_mov_b64_e32 v[26:27], 0
	v_mov_b64_e32 v[28:29], 0
	v_mov_b64_e32 v[30:31], 0
	v_mov_b64_e32 v[32:33], 0
	v_mov_b64_e32 v[34:35], 0
	v_mov_b64_e32 v[36:37], 0
	v_mov_b64_e32 v[38:39], 0
	v_mov_b64_e32 v[40:41], 0
	v_mov_b64_e32 v[42:43], 0
	v_mov_b64_e32 v[44:45], 0
	v_mov_b64_e32 v[46:47], 0
	v_mov_b64_e32 v[48:49], 0
	v_mov_b64_e32 v[50:51], 0
	v_mov_b64_e32 v[52:53], 0
	v_mov_b64_e32 v[54:55], 0
	v_mov_b64_e32 v[56:57], 0
	v_mov_b64_e32 v[58:59], 0
	v_mov_b64_e32 v[60:61], 0
	v_mov_b64_e32 v[62:63], 0
	v_mov_b64_e32 v[64:65], 0
	v_mov_b64_e32 v[66:67], 0
	v_mov_b64_e32 v[68:69], 0
	v_mov_b64_e32 v[70:71], 0
	v_mov_b64_e32 v[72:73], 0
	v_mov_b64_e32 v[74:75], 0
	v_mov_b64_e32 v[76:77], 0
	v_mov_b64_e32 v[78:79], 0
	v_mov_b64_e32 v[80:81], 0
	v_mov_b64_e32 v[82:83], 0
	v_mov_b64_e32 v[84:85], 0
	v_mov_b64_e32 v[86:87], 0
	v_mov_b64_e32 v[88:89], 0
	v_mov_b64_e32 v[90:91], 0
	v_mov_b64_e32 v[92:93], 0
	v_mov_b64_e32 v[94:95], 0
	v_mov_b64_e32 v[96:97], 0
	v_mov_b64_e32 v[98:99], 0
	v_mov_b64_e32 v[100:101], 0
	v_mov_b64_e32 v[102:103], 0
	v_mov_b64_e32 v[104:105], 0
	v_mov_b64_e32 v[106:107], 0
	v_mov_b64_e32 v[108:109], 0
	v_mov_b64_e32 v[110:111], 0
	v_mov_b64_e32 v[112:113], 0
	v_mov_b64_e32 v[114:115], 0
	v_mov_b64_e32 v[116:117], 0
	v_mov_b64_e32 v[118:119], 0
	v_mov_b64_e32 v[120:121], 0
	v_mov_b64_e32 v[122:123], 0
	v_mov_b64_e32 v[124:125], 0
	v_mov_b64_e32 v[126:127], 0
	v_mov_b64_e32 v[128:129], 0
	s_addc_u32 s55, s39, 0
	s_mov_b32 s57, -2
	s_waitcnt vmcnt(0)

; template <class Epi, class Sched, bool ALIGN_EPI = false, bool SP2 = false>
; __device__ __forceinline__ void gemm_phase(PG8_LAS unsigned char* lds, const Gemm g, const Sched& S, const Epi& E) {
;     ...
;         const bool has_next = S.next(ui + 1, nxt);
;         const char* nA = has_next ? (const char*)g.A + (size_t)nxt.pm * tstep : cA; const char* nB = has_next ? (const char*)g.Bt + (size_t)nxt.pn * tstep : cB;
;         for (int t = 0; t < nt; t += 2) {
;             const bool last = (t == nt - 2);
;             const char* a1 = cA + (size_t)(t + 1) * kstep;
;             const char* a2 = last ? nA : cA + (size_t)(t + 2) * kstep; const char* b2 = last ? nB : cB + (size_t)(t + 2) * kstep;
;             const char* a3 = a2 + kstep; const char* b3 = b2 + kstep;
;     ...
; #pragma unroll
;         for (int a = 0; a < 2; ++a)
; #pragma unroll
;             for (int b = 0; b < 2; ++b)
; #pragma unroll
;                 for (int m = 0; m < 4; ++m)
; #pragma unroll
;                     for (int n = 0; n < 2; ++n) acc[a][b][m][n] = (f32x4){0.f, 0.f, 0.f, 0.f};
;         cur = nxt; cA = nA; cB = nB; ++ui;
.LBB0_325:
	s_ashr_i32 s39, s38, 31
	s_lshl_b64 s[24:25], s[38:39], 19
	s_add_u32 s44, s15, s24
	s_addc_u32 s45, s26, s25
	s_and_b64 s[24:25], s[4:5], exec
	s_cselect_b32 s31, s45, s21
	s_cselect_b32 s39, s44, s20
	s_ashr_i32 s17, s16, 31
	s_lshl_b64 s[24:25], s[16:17], 19
	s_add_u32 s46, s10, s24
	s_addc_u32 s47, s11, s25
	s_and_b64 s[24:25], s[4:5], exec
	s_cselect_b32 s17, s47, s23
	s_cselect_b32 s43, s46, s22
	s_add_u32 s20, s20, 0x40080
	s_addc_u32 s21, s21, 0
	s_add_u32 s62, s22, 0x100
	v_mov_b64_e32 v[2:3], 0
	v_mov_b64_e32 v[4:5], 0
	v_mov_b64_e32 v[6:7], 0
	v_mov_b64_e32 v[8:9], 0
	v_mov_b64_e32 v[10:11], 0
	v_mov_b64_e32 v[12:13], 0
	v_mov_b64_e32 v[14:15], 0
	v_mov_b64_e32 v[16:17], 0
	v_mov_b64_e32 v[18:19], 0
	v_mov_b64_e32 v[20:21], 0
	v_mov_b64_e32 v[22:23], 0
	v_mov_b64_e32 v[24:25], 0
	v_mov_b64_e32 v[26:27], 0
	v_mov_b64_e32 v[28:29], 0
	v_mov_b64_e32 v[30:31], 0
	v_mov_b64_e32 v[32:33], 0
	v_mov_b64_e32 v[34:35], 0
	v_mov_b64_e32 v[36:37], 0
	v_mov_b64_e32 v[38:39], 0
	v_mov_b64_e32 v[40:41], 0
	v_mov_b64_e32 v[42:43], 0
	v_mov_b64_e32 v[44:45], 0
	v_mov_b64_e32 v[46:47], 0
	v_mov_b64_e32 v[48:49], 0
	v_mov_b64_e32 v[50:51], 0
	v_mov_b64_e32 v[52:53], 0
	v_mov_b64_e32 v[54:55], 0
	v_mov_b64_e32 v[56:57], 0
	v_mov_b64_e32 v[58:59], 0
	v_mov_b64_e32 v[60:61], 0
	v_mov_b64_e32 v[62:63], 0
	v_mov_b64_e32 v[64:65], 0
	v_mov_b64_e32 v[66:67], 0
	v_mov_b64_e32 v[68:69], 0
	v_mov_b64_e32 v[70:71], 0
	v_mov_b64_e32 v[72:73], 0
	v_mov_b64_e32 v[74:75], 0
	v_mov_b64_e32 v[76:77], 0
	v_mov_b64_e32 v[78:79], 0
	v_mov_b64_e32 v[80:81], 0
	v_mov_b64_e32 v[82:83], 0
	v_mov_b64_e32 v[84:85], 0
	v_mov_b64_e32 v[86:87], 0
	v_mov_b64_e32 v[88:89], 0
	v_mov_b64_e32 v[90:91], 0
	v_mov_b64_e32 v[92:93], 0
	v_mov_b64_e32 v[94:95], 0
	v_mov_b64_e32 v[96:97], 0
	v_mov_b64_e32 v[98:99], 0
	v_mov_b64_e32 v[100:101], 0
	v_mov_b64_e32 v[102:103], 0
	v_mov_b64_e32 v[104:105], 0
	v_mov_b64_e32 v[106:107], 0
	v_mov_b64_e32 v[108:109], 0
	v_mov_b64_e32 v[110:111], 0
	v_mov_b64_e32 v[112:113], 0
	v_mov_b64_e32 v[114:115], 0
	v_mov_b64_e32 v[116:117], 0
	v_mov_b64_e32 v[118:119], 0
	v_mov_b64_e32 v[120:121], 0
	v_mov_b64_e32 v[122:123], 0
	v_mov_b64_e32 v[124:125], 0
	v_mov_b64_e32 v[126:127], 0
	v_mov_b64_e32 v[128:129], 0
	s_addc_u32 s69, s23, 0
	s_mov_b32 s70, -2

; template <class Epi, class Sched, bool ALIGN_EPI = false, bool SP2 = false>
; __device__ __forceinline__ void gemm_phase(PG8_LAS unsigned char* lds, const Gemm g, const Sched& S, const Epi& E) {
;     ...
;         const bool has_next = S.next(ui + 1, nxt);
;         const char* nA = has_next ? (const char*)g.A + (size_t)nxt.pm * tstep : cA; const char* nB = has_next ? (const char*)g.Bt + (size_t)nxt.pn * tstep : cB;
;         for (int t = 0; t < nt; t += 2) {
;             const bool last = (t == nt - 2);
;             const char* a1 = cA + (size_t)(t + 1) * kstep;
;             const char* a2 = last ? nA : cA + (size_t)(t + 2) * kstep; const char* b2 = last ? nB : cB + (size_t)(t + 2) * kstep;
;             const char* a3 = a2 + kstep; const char* b3 = b2 + kstep;
;     ...
; #pragma unroll
;         for (int a = 0; a < 2; ++a)
; #pragma unroll
;             for (int b = 0; b < 2; ++b)
; #pragma unroll
;                 for (int m = 0; m < 4; ++m)
; #pragma unroll
;                     for (int n = 0; n < 2; ++n) acc[a][b][m][n] = (f32x4){0.f, 0.f, 0.f, 0.f};
;         cur = nxt; cA = nA; cB = nB; ++ui;
.LBB0_406:
	s_ashr_i32 s49, s48, 31
	s_lshl_b64 s[22:23], s[48:49], 19
	s_add_u32 s38, s53, s22
	s_addc_u32 s39, s64, s23
	s_and_b64 s[22:23], s[4:5], exec
	s_cselect_b32 s25, s39, s7
	s_cselect_b32 s30, s38, s6
	s_ashr_i32 s47, s46, 31
	s_lshl_b64 s[22:23], s[46:47], 19
	s_add_u32 s50, s26, s22
	s_addc_u32 s51, s27, s23
	s_and_b64 s[22:23], s[4:5], exec
	s_cselect_b32 s31, s51, s21
	s_cselect_b32 s43, s50, s20
	s_add_u32 s6, s6, 0x40080
	s_addc_u32 s7, s7, 0
	s_add_u32 s47, s20, 0x100
	v_mov_b64_e32 v[2:3], 0
	v_mov_b64_e32 v[4:5], 0
	v_mov_b64_e32 v[6:7], 0
	v_mov_b64_e32 v[8:9], 0
	v_mov_b64_e32 v[10:11], 0
	v_mov_b64_e32 v[12:13], 0
	v_mov_b64_e32 v[14:15], 0
	v_mov_b64_e32 v[16:17], 0
	v_mov_b64_e32 v[18:19], 0
	v_mov_b64_e32 v[20:21], 0
	v_mov_b64_e32 v[22:23], 0
	v_mov_b64_e32 v[24:25], 0
	v_mov_b64_e32 v[26:27], 0
	v_mov_b64_e32 v[28:29], 0
	v_mov_b64_e32 v[30:31], 0
	v_mov_b64_e32 v[32:33], 0
	v_mov_b64_e32 v[34:35], 0
	v_mov_b64_e32 v[36:37], 0
	v_mov_b64_e32 v[38:39], 0
	v_mov_b64_e32 v[40:41], 0
	v_mov_b64_e32 v[42:43], 0
	v_mov_b64_e32 v[44:45], 0
	v_mov_b64_e32 v[46:47], 0
	v_mov_b64_e32 v[48:49], 0
	v_mov_b64_e32 v[50:51], 0
	v_mov_b64_e32 v[52:53], 0
	v_mov_b64_e32 v[54:55], 0
	v_mov_b64_e32 v[56:57], 0
	v_mov_b64_e32 v[58:59], 0
	v_mov_b64_e32 v[60:61], 0
	v_mov_b64_e32 v[62:63], 0
	v_mov_b64_e32 v[64:65], 0
	v_mov_b64_e32 v[66:67], 0
	v_mov_b64_e32 v[68:69], 0
	v_mov_b64_e32 v[70:71], 0
	v_mov_b64_e32 v[72:73], 0
	v_mov_b64_e32 v[74:75], 0
	v_mov_b64_e32 v[76:77], 0
	v_mov_b64_e32 v[78:79], 0
	v_mov_b64_e32 v[80:81], 0
	v_mov_b64_e32 v[82:83], 0
	v_mov_b64_e32 v[84:85], 0
	v_mov_b64_e32 v[86:87], 0
	v_mov_b64_e32 v[88:89], 0
	v_mov_b64_e32 v[90:91], 0
	v_mov_b64_e32 v[92:93], 0
	v_mov_b64_e32 v[94:95], 0
	v_mov_b64_e32 v[96:97], 0
	v_mov_b64_e32 v[98:99], 0
	v_mov_b64_e32 v[100:101], 0
	v_mov_b64_e32 v[102:103], 0
	v_mov_b64_e32 v[104:105], 0
	v_mov_b64_e32 v[106:107], 0
	v_mov_b64_e32 v[108:109], 0
	v_mov_b64_e32 v[110:111], 0
	v_mov_b64_e32 v[112:113], 0
	v_mov_b64_e32 v[114:115], 0
	v_mov_b64_e32 v[116:117], 0
	v_mov_b64_e32 v[118:119], 0
	v_mov_b64_e32 v[120:121], 0
	v_mov_b64_e32 v[122:123], 0
	v_mov_b64_e32 v[124:125], 0
	v_mov_b64_e32 v[126:127], 0
	v_mov_b64_e32 v[128:129], 0
	s_addc_u32 s49, s21, 0
	s_mov_b32 s62, -2

; template <class Epi, class Sched, bool ALIGN_EPI = false, bool SP2 = false>
; __device__ __forceinline__ void gemm_phase(PG8_LAS unsigned char* lds, const Gemm g, const Sched& S, const Epi& E) {
;     ...
;         const bool has_next = S.next(ui + 1, nxt);
;         const char* nA = has_next ? (const char*)g.A + (size_t)nxt.pm * tstep : cA; const char* nB = has_next ? (const char*)g.Bt + (size_t)nxt.pn * tstep : cB;
;         for (int t = 0; t < nt; t += 2) {
;             const bool last = (t == nt - 2);
;             const char* a1 = cA + (size_t)(t + 1) * kstep;
;             const char* a2 = last ? nA : cA + (size_t)(t + 2) * kstep; const char* b2 = last ? nB : cB + (size_t)(t + 2) * kstep;
;             const char* a3 = a2 + kstep; const char* b3 = b2 + kstep;
;     ...
; #pragma unroll
;         for (int a = 0; a < 2; ++a)
; #pragma unroll
;             for (int b = 0; b < 2; ++b)
; #pragma unroll
;                 for (int m = 0; m < 4; ++m)
; #pragma unroll
;                     for (int n = 0; n < 2; ++n) acc[a][b][m][n] = (f32x4){0.f, 0.f, 0.f, 0.f};
;         cur = nxt; cA = nA; cB = nB; ++ui;
.LBB0_769:
	s_ashr_i32 s21, s20, 31
	s_lshl_b64 s[4:5], s[20:21], 19
	s_add_u32 s22, s14, s4
	s_addc_u32 s23, s15, s5
	s_and_b64 s[4:5], s[6:7], exec
	s_cselect_b32 s21, s23, s27
	s_cselect_b32 s53, s22, s26
	s_ashr_i32 s17, s16, 31
	s_lshl_b64 s[4:5], s[16:17], 19
	s_add_u32 s24, s28, s4
	s_addc_u32 s25, s30, s5
	s_and_b64 s[4:5], s[6:7], exec
	s_cselect_b32 s17, s25, s39
	s_cselect_b32 s54, s24, s38
	s_add_u32 s26, s26, 0x40080
	s_addc_u32 s27, s27, 0
	s_add_u32 s55, s38, 0x100
	v_mov_b64_e32 v[2:3], 0
	v_mov_b64_e32 v[4:5], 0
	v_mov_b64_e32 v[6:7], 0
	v_mov_b64_e32 v[8:9], 0
	v_mov_b64_e32 v[10:11], 0
	v_mov_b64_e32 v[12:13], 0
	v_mov_b64_e32 v[14:15], 0
	v_mov_b64_e32 v[16:17], 0
	v_mov_b64_e32 v[18:19], 0
	v_mov_b64_e32 v[20:21], 0
	v_mov_b64_e32 v[22:23], 0
	v_mov_b64_e32 v[24:25], 0
	v_mov_b64_e32 v[26:27], 0
	v_mov_b64_e32 v[28:29], 0
	v_mov_b64_e32 v[30:31], 0
	v_mov_b64_e32 v[32:33], 0
	v_mov_b64_e32 v[34:35], 0
	v_mov_b64_e32 v[36:37], 0
	v_mov_b64_e32 v[38:39], 0
	v_mov_b64_e32 v[40:41], 0
	v_mov_b64_e32 v[42:43], 0
	v_mov_b64_e32 v[44:45], 0
	v_mov_b64_e32 v[46:47], 0
	v_mov_b64_e32 v[48:49], 0
	v_mov_b64_e32 v[50:51], 0
	v_mov_b64_e32 v[52:53], 0
	v_mov_b64_e32 v[54:55], 0
	v_mov_b64_e32 v[56:57], 0
	v_mov_b64_e32 v[58:59], 0
	v_mov_b64_e32 v[60:61], 0
	v_mov_b64_e32 v[62:63], 0
	v_mov_b64_e32 v[64:65], 0
	v_mov_b64_e32 v[66:67], 0
	v_mov_b64_e32 v[68:69], 0
	v_mov_b64_e32 v[70:71], 0
	v_mov_b64_e32 v[72:73], 0
	v_mov_b64_e32 v[74:75], 0
	v_mov_b64_e32 v[76:77], 0
	v_mov_b64_e32 v[78:79], 0
	v_mov_b64_e32 v[80:81], 0
	v_mov_b64_e32 v[82:83], 0
	v_mov_b64_e32 v[84:85], 0
	v_mov_b64_e32 v[86:87], 0
	v_mov_b64_e32 v[88:89], 0
	v_mov_b64_e32 v[90:91], 0
	v_mov_b64_e32 v[92:93], 0
	v_mov_b64_e32 v[94:95], 0
	v_mov_b64_e32 v[96:97], 0
	v_mov_b64_e32 v[98:99], 0
	v_mov_b64_e32 v[100:101], 0
	v_mov_b64_e32 v[102:103], 0
	v_mov_b64_e32 v[104:105], 0
	v_mov_b64_e32 v[106:107], 0
	v_mov_b64_e32 v[108:109], 0
	v_mov_b64_e32 v[110:111], 0
	v_mov_b64_e32 v[112:113], 0
	v_mov_b64_e32 v[114:115], 0
	v_mov_b64_e32 v[116:117], 0
	v_mov_b64_e32 v[118:119], 0
	v_mov_b64_e32 v[120:121], 0
	v_mov_b64_e32 v[122:123], 0
	v_mov_b64_e32 v[124:125], 0
	v_mov_b64_e32 v[126:127], 0
	v_mov_b64_e32 v[128:129], 0
	s_addc_u32 s4, s39, 0
	s_mov_b32 s5, -2
	s_waitcnt vmcnt(0)

; template <class Epi, class Sched, bool ALIGN_EPI = false, bool SP2 = false>
; __device__ __forceinline__ void gemm_phase(PG8_LAS unsigned char* lds, const Gemm g, const Sched& S, const Epi& E) {
;     ...
;         const bool has_next = S.next(ui + 1, nxt);
;         const char* nA = has_next ? (const char*)g.A + (size_t)nxt.pm * tstep : cA; const char* nB = has_next ? (const char*)g.Bt + (size_t)nxt.pn * tstep : cB;
;         for (int t = 0; t < nt; t += 2) {
;             const bool last = (t == nt - 2);
;             const char* a1 = cA + (size_t)(t + 1) * kstep;
;             const char* a2 = last ? nA : cA + (size_t)(t + 2) * kstep; const char* b2 = last ? nB : cB + (size_t)(t + 2) * kstep;
;             const char* a3 = a2 + kstep; const char* b3 = b2 + kstep;
;     ...
; #pragma unroll
;         for (int a = 0; a < 2; ++a)
; #pragma unroll
;             for (int b = 0; b < 2; ++b)
; #pragma unroll
;                 for (int m = 0; m < 4; ++m)
; #pragma unroll
;                     for (int n = 0; n < 2; ++n) acc[a][b][m][n] = (f32x4){0.f, 0.f, 0.f, 0.f};
;         cur = nxt; cA = nA; cB = nB; ++ui;
.LBB0_901:
	s_ashr_i32 s17, s16, 31
	s_lshl_b64 s[4:5], s[16:17], 19
	s_add_u32 s20, s30, s4
	s_addc_u32 s21, s31, s5
	s_and_b64 s[4:5], s[6:7], exec
	s_cselect_b32 s17, s21, s25
	s_cselect_b32 s52, s20, s24
	s_ashr_i32 s13, s12, 31
	s_lshl_b64 s[4:5], s[12:13], 19
	s_add_u32 s22, s14, s4
	s_addc_u32 s23, s15, s5
	s_and_b64 s[4:5], s[6:7], exec
	s_cselect_b32 s13, s23, s27
	s_cselect_b32 s53, s22, s26
	s_add_u32 s24, s24, 0x40080
	s_addc_u32 s25, s25, 0
	s_add_u32 s54, s26, 0x100
	v_mov_b64_e32 v[2:3], 0
	v_mov_b64_e32 v[4:5], 0
	v_mov_b64_e32 v[6:7], 0
	v_mov_b64_e32 v[8:9], 0
	v_mov_b64_e32 v[10:11], 0
	v_mov_b64_e32 v[12:13], 0
	v_mov_b64_e32 v[14:15], 0
	v_mov_b64_e32 v[16:17], 0
	v_mov_b64_e32 v[18:19], 0
	v_mov_b64_e32 v[20:21], 0
	v_mov_b64_e32 v[22:23], 0
	v_mov_b64_e32 v[24:25], 0
	v_mov_b64_e32 v[26:27], 0
	v_mov_b64_e32 v[28:29], 0
	v_mov_b64_e32 v[30:31], 0
	v_mov_b64_e32 v[32:33], 0
	v_mov_b64_e32 v[34:35], 0
	v_mov_b64_e32 v[36:37], 0
	v_mov_b64_e32 v[38:39], 0
	v_mov_b64_e32 v[40:41], 0
	v_mov_b64_e32 v[42:43], 0
	v_mov_b64_e32 v[44:45], 0
	v_mov_b64_e32 v[46:47], 0
	v_mov_b64_e32 v[48:49], 0
	v_mov_b64_e32 v[50:51], 0
	v_mov_b64_e32 v[52:53], 0
	v_mov_b64_e32 v[54:55], 0
	v_mov_b64_e32 v[56:57], 0
	v_mov_b64_e32 v[58:59], 0
	v_mov_b64_e32 v[60:61], 0
	v_mov_b64_e32 v[62:63], 0
	v_mov_b64_e32 v[64:65], 0
	v_mov_b64_e32 v[66:67], 0
	v_mov_b64_e32 v[68:69], 0
	v_mov_b64_e32 v[70:71], 0
	v_mov_b64_e32 v[72:73], 0
	v_mov_b64_e32 v[74:75], 0
	v_mov_b64_e32 v[76:77], 0
	v_mov_b64_e32 v[78:79], 0
	v_mov_b64_e32 v[80:81], 0
	v_mov_b64_e32 v[82:83], 0
	v_mov_b64_e32 v[84:85], 0
	v_mov_b64_e32 v[86:87], 0
	v_mov_b64_e32 v[88:89], 0
	v_mov_b64_e32 v[90:91], 0
	v_mov_b64_e32 v[92:93], 0
	v_mov_b64_e32 v[94:95], 0
	v_mov_b64_e32 v[96:97], 0
	v_mov_b64_e32 v[98:99], 0
	v_mov_b64_e32 v[100:101], 0
	v_mov_b64_e32 v[102:103], 0
	v_mov_b64_e32 v[104:105], 0
	v_mov_b64_e32 v[106:107], 0
	v_mov_b64_e32 v[108:109], 0
	v_mov_b64_e32 v[110:111], 0
	v_mov_b64_e32 v[112:113], 0
	v_mov_b64_e32 v[114:115], 0
	v_mov_b64_e32 v[116:117], 0
	v_mov_b64_e32 v[118:119], 0
	v_mov_b64_e32 v[120:121], 0
	v_mov_b64_e32 v[122:123], 0
	v_mov_b64_e32 v[124:125], 0
	v_mov_b64_e32 v[126:127], 0
	v_mov_b64_e32 v[128:129], 0
	s_addc_u32 s4, s27, 0
	s_mov_b32 s5, -2

; template <class Epi, class Sched, bool ALIGN_EPI = false, bool SP2 = false>
; __device__ __forceinline__ void gemm_phase(PG8_LAS unsigned char* lds, const Gemm g, const Sched& S, const Epi& E) {
;     ...
;         const bool has_next = S.next(ui + 1, nxt);
;         const char* nA = has_next ? (const char*)g.A + (size_t)nxt.pm * tstep : cA; const char* nB = has_next ? (const char*)g.Bt + (size_t)nxt.pn * tstep : cB;
;         for (int t = 0; t < nt; t += 2) {
;             const bool last = (t == nt - 2);
;             const char* a1 = cA + (size_t)(t + 1) * kstep;
;             const char* a2 = last ? nA : cA + (size_t)(t + 2) * kstep; const char* b2 = last ? nB : cB + (size_t)(t + 2) * kstep;
;             const char* a3 = a2 + kstep; const char* b3 = b2 + kstep;
;     ...
; #pragma unroll
;         for (int a = 0; a < 2; ++a)
; #pragma unroll
;             for (int b = 0; b < 2; ++b)
; #pragma unroll
;                 for (int m = 0; m < 4; ++m)
; #pragma unroll
;                     for (int n = 0; n < 2; ++n) acc[a][b][m][n] = (f32x4){0.f, 0.f, 0.f, 0.f};
;         cur = nxt; cA = nA; cB = nB; ++ui;
.LBB0_1062:
	s_ashr_i32 s21, s20, 31
	s_lshl_b64 s[4:5], s[20:21], 18
	s_add_u32 s22, s14, s4
	s_addc_u32 s23, s15, s5
	s_and_b64 s[4:5], s[6:7], exec
	s_cselect_b32 s21, s23, s27
	s_cselect_b32 s53, s22, s26
	s_ashr_i32 s17, s16, 31
	s_lshl_b64 s[4:5], s[16:17], 18
	s_add_u32 s24, s28, s4
	s_addc_u32 s25, s30, s5
	s_and_b64 s[4:5], s[6:7], exec
	s_cselect_b32 s17, s25, s39
	s_cselect_b32 s54, s24, s38
	s_add_u32 s26, s26, 0x20080
	s_addc_u32 s27, s27, 0
	s_add_u32 s55, s38, 0x100
	v_mov_b64_e32 v[2:3], 0
	v_mov_b64_e32 v[4:5], 0
	v_mov_b64_e32 v[6:7], 0
	v_mov_b64_e32 v[8:9], 0
	v_mov_b64_e32 v[10:11], 0
	v_mov_b64_e32 v[12:13], 0
	v_mov_b64_e32 v[14:15], 0
	v_mov_b64_e32 v[16:17], 0
	v_mov_b64_e32 v[18:19], 0
	v_mov_b64_e32 v[20:21], 0
	v_mov_b64_e32 v[22:23], 0
	v_mov_b64_e32 v[24:25], 0
	v_mov_b64_e32 v[26:27], 0
	v_mov_b64_e32 v[28:29], 0
	v_mov_b64_e32 v[30:31], 0
	v_mov_b64_e32 v[32:33], 0
	v_mov_b64_e32 v[34:35], 0
	v_mov_b64_e32 v[36:37], 0
	v_mov_b64_e32 v[38:39], 0
	v_mov_b64_e32 v[40:41], 0
	v_mov_b64_e32 v[42:43], 0
	v_mov_b64_e32 v[44:45], 0
	v_mov_b64_e32 v[46:47], 0
	v_mov_b64_e32 v[48:49], 0
	v_mov_b64_e32 v[50:51], 0
	v_mov_b64_e32 v[52:53], 0
	v_mov_b64_e32 v[54:55], 0
	v_mov_b64_e32 v[56:57], 0
	v_mov_b64_e32 v[58:59], 0
	v_mov_b64_e32 v[60:61], 0
	v_mov_b64_e32 v[62:63], 0
	v_mov_b64_e32 v[64:65], 0
	v_mov_b64_e32 v[66:67], 0
	v_mov_b64_e32 v[68:69], 0
	v_mov_b64_e32 v[70:71], 0
	v_mov_b64_e32 v[72:73], 0
	v_mov_b64_e32 v[74:75], 0
	v_mov_b64_e32 v[76:77], 0
	v_mov_b64_e32 v[78:79], 0
	v_mov_b64_e32 v[80:81], 0
	v_mov_b64_e32 v[82:83], 0
	v_mov_b64_e32 v[84:85], 0
	v_mov_b64_e32 v[86:87], 0
	v_mov_b64_e32 v[88:89], 0
	v_mov_b64_e32 v[90:91], 0
	v_mov_b64_e32 v[92:93], 0
	v_mov_b64_e32 v[94:95], 0
	v_mov_b64_e32 v[96:97], 0
	v_mov_b64_e32 v[98:99], 0
	v_mov_b64_e32 v[100:101], 0
	v_mov_b64_e32 v[102:103], 0
	v_mov_b64_e32 v[104:105], 0
	v_mov_b64_e32 v[106:107], 0
	v_mov_b64_e32 v[108:109], 0
	v_mov_b64_e32 v[110:111], 0
	v_mov_b64_e32 v[112:113], 0
	v_mov_b64_e32 v[114:115], 0
	v_mov_b64_e32 v[116:117], 0
	v_mov_b64_e32 v[118:119], 0
	v_mov_b64_e32 v[120:121], 0
	v_mov_b64_e32 v[122:123], 0
	v_mov_b64_e32 v[124:125], 0
	v_mov_b64_e32 v[126:127], 0
	v_mov_b64_e32 v[128:129], 0
	s_addc_u32 s4, s39, 0
	s_mov_b32 s5, -2
	s_waitcnt vmcnt(0)

; template <class Epi, class Sched, bool ALIGN_EPI = false, bool SP2 = false>
; __device__ __forceinline__ void gemm_phase(PG8_LAS unsigned char* lds, const Gemm g, const Sched& S, const Epi& E) {
;     ...
;         const bool has_next = S.next(ui + 1, nxt);
;         const char* nA = has_next ? (const char*)g.A + (size_t)nxt.pm * tstep : cA; const char* nB = has_next ? (const char*)g.Bt + (size_t)nxt.pn * tstep : cB;
;         for (int t = 0; t < nt; t += 2) {
;             const bool last = (t == nt - 2);
;             const char* a1 = cA + (size_t)(t + 1) * kstep;
;             const char* a2 = last ? nA : cA + (size_t)(t + 2) * kstep; const char* b2 = last ? nB : cB + (size_t)(t + 2) * kstep;
;             const char* a3 = a2 + kstep; const char* b3 = b2 + kstep;
;     ...
; #pragma unroll
;         for (int a = 0; a < 2; ++a)
; #pragma unroll
;             for (int b = 0; b < 2; ++b)
; #pragma unroll
;                 for (int m = 0; m < 4; ++m)
; #pragma unroll
;                     for (int n = 0; n < 2; ++n) acc[a][b][m][n] = (f32x4){0.f, 0.f, 0.f, 0.f};
;         cur = nxt; cA = nA; cB = nB; ++ui;
.LBB0_1174:
	s_ashr_i32 s27, s26, 31
	s_lshl_b64 s[4:5], s[26:27], 19
	s_add_u32 s64, s33, s4
	s_addc_u32 s65, s36, s5
	s_and_b64 s[4:5], s[6:7], exec
	s_cselect_b32 s27, s65, s1
	s_cselect_b32 vcc_lo, s64, s0
	s_ashr_i32 s25, s24, 31
	s_lshl_b64 s[4:5], s[24:25], 19
	s_add_u32 s66, s14, s4
	s_addc_u32 s67, s15, s5
	s_and_b64 s[4:5], s[6:7], exec
	s_cselect_b32 s25, s67, s9
	s_cselect_b32 vcc_hi, s66, s8
	s_add_u32 s0, s0, 0x40080
	s_addc_u32 s1, s1, 0
	s_add_u32 s4, s8, 0x100
	v_mov_b64_e32 v[2:3], 0
	v_mov_b64_e32 v[4:5], 0
	v_mov_b64_e32 v[6:7], 0
	v_mov_b64_e32 v[8:9], 0
	v_mov_b64_e32 v[10:11], 0
	v_mov_b64_e32 v[12:13], 0
	v_mov_b64_e32 v[14:15], 0
	v_mov_b64_e32 v[16:17], 0
	v_mov_b64_e32 v[18:19], 0
	v_mov_b64_e32 v[20:21], 0
	v_mov_b64_e32 v[22:23], 0
	v_mov_b64_e32 v[24:25], 0
	v_mov_b64_e32 v[26:27], 0
	v_mov_b64_e32 v[28:29], 0
	v_mov_b64_e32 v[30:31], 0
	v_mov_b64_e32 v[32:33], 0
	v_mov_b64_e32 v[34:35], 0
	v_mov_b64_e32 v[36:37], 0
	v_mov_b64_e32 v[38:39], 0
	v_mov_b64_e32 v[40:41], 0
	v_mov_b64_e32 v[42:43], 0
	v_mov_b64_e32 v[44:45], 0
	v_mov_b64_e32 v[46:47], 0
	v_mov_b64_e32 v[48:49], 0
	v_mov_b64_e32 v[50:51], 0
	v_mov_b64_e32 v[52:53], 0
	v_mov_b64_e32 v[54:55], 0
	v_mov_b64_e32 v[56:57], 0
	v_mov_b64_e32 v[58:59], 0
	v_mov_b64_e32 v[60:61], 0
	v_mov_b64_e32 v[62:63], 0
	v_mov_b64_e32 v[64:65], 0
	v_mov_b64_e32 v[66:67], 0
	v_mov_b64_e32 v[68:69], 0
	v_mov_b64_e32 v[70:71], 0
	v_mov_b64_e32 v[72:73], 0
	v_mov_b64_e32 v[74:75], 0
	v_mov_b64_e32 v[76:77], 0
	v_mov_b64_e32 v[78:79], 0
	v_mov_b64_e32 v[80:81], 0
	v_mov_b64_e32 v[82:83], 0
	v_mov_b64_e32 v[84:85], 0
	v_mov_b64_e32 v[86:87], 0
	v_mov_b64_e32 v[88:89], 0
	v_mov_b64_e32 v[90:91], 0
	v_mov_b64_e32 v[92:93], 0
	v_mov_b64_e32 v[94:95], 0
	v_mov_b64_e32 v[96:97], 0
	v_mov_b64_e32 v[98:99], 0
	v_mov_b64_e32 v[100:101], 0
	v_mov_b64_e32 v[102:103], 0
	v_mov_b64_e32 v[104:105], 0
	v_mov_b64_e32 v[106:107], 0
	v_mov_b64_e32 v[108:109], 0
	v_mov_b64_e32 v[110:111], 0
	v_mov_b64_e32 v[112:113], 0
	v_mov_b64_e32 v[114:115], 0
	v_mov_b64_e32 v[116:117], 0
	v_mov_b64_e32 v[118:119], 0
	v_mov_b64_e32 v[120:121], 0
	v_mov_b64_e32 v[122:123], 0
	v_mov_b64_e32 v[124:125], 0
	v_mov_b64_e32 v[126:127], 0
	v_mov_b64_e32 v[128:129], 0
	s_addc_u32 s5, s9, 0
	s_mov_b32 s37, -2

; template <class Epi, class Sched, bool ALIGN_EPI = false, bool SP2 = false>
; __device__ __forceinline__ void gemm_phase(PG8_LAS unsigned char* lds, const Gemm g, const Sched& S, const Epi& E) {
;     ...
;         const bool has_next = S.next(ui + 1, nxt);
;         const char* nA = has_next ? (const char*)g.A + (size_t)nxt.pm * tstep : cA; const char* nB = has_next ? (const char*)g.Bt + (size_t)nxt.pn * tstep : cB;
;         for (int t = 0; t < nt; t += 2) {
;             const bool last = (t == nt - 2);
;             const char* a1 = cA + (size_t)(t + 1) * kstep;
;             const char* a2 = last ? nA : cA + (size_t)(t + 2) * kstep; const char* b2 = last ? nB : cB + (size_t)(t + 2) * kstep;
;             const char* a3 = a2 + kstep; const char* b3 = b2 + kstep;
;     ...
; #pragma unroll
;         for (int a = 0; a < 2; ++a)
; #pragma unroll
;             for (int b = 0; b < 2; ++b)
; #pragma unroll
;                 for (int m = 0; m < 4; ++m)
; #pragma unroll
;                     for (int n = 0; n < 2; ++n) acc[a][b][m][n] = (f32x4){0.f, 0.f, 0.f, 0.f};
;         cur = nxt; cA = nA; cB = nB; ++ui;
.LBB0_1297:
	s_add_u32 s4, s26, 0x100
	v_mov_b64_e32 v[2:3], 0
	v_mov_b64_e32 v[4:5], 0
	v_mov_b64_e32 v[6:7], 0
	v_mov_b64_e32 v[8:9], 0
	v_mov_b64_e32 v[10:11], 0
	v_mov_b64_e32 v[12:13], 0
	v_mov_b64_e32 v[14:15], 0
	v_mov_b64_e32 v[16:17], 0
	v_mov_b64_e32 v[18:19], 0
	v_mov_b64_e32 v[20:21], 0
	v_mov_b64_e32 v[22:23], 0
	v_mov_b64_e32 v[24:25], 0
	v_mov_b64_e32 v[26:27], 0
	v_mov_b64_e32 v[28:29], 0
	v_mov_b64_e32 v[30:31], 0
	v_mov_b64_e32 v[32:33], 0
	v_mov_b64_e32 v[34:35], 0
	v_mov_b64_e32 v[36:37], 0
	v_mov_b64_e32 v[38:39], 0
	v_mov_b64_e32 v[40:41], 0
	v_mov_b64_e32 v[42:43], 0
	v_mov_b64_e32 v[44:45], 0
	v_mov_b64_e32 v[46:47], 0
	v_mov_b64_e32 v[48:49], 0
	v_mov_b64_e32 v[50:51], 0
	v_mov_b64_e32 v[52:53], 0
	v_mov_b64_e32 v[54:55], 0
	v_mov_b64_e32 v[56:57], 0
	v_mov_b64_e32 v[58:59], 0
	v_mov_b64_e32 v[60:61], 0
	v_mov_b64_e32 v[62:63], 0
	v_mov_b64_e32 v[64:65], 0
	v_mov_b64_e32 v[66:67], 0
	v_mov_b64_e32 v[68:69], 0
	v_mov_b64_e32 v[70:71], 0
	v_mov_b64_e32 v[72:73], 0
	v_mov_b64_e32 v[74:75], 0
	v_mov_b64_e32 v[76:77], 0
	v_mov_b64_e32 v[78:79], 0
	v_mov_b64_e32 v[80:81], 0
	v_mov_b64_e32 v[82:83], 0
	v_mov_b64_e32 v[84:85], 0
	v_mov_b64_e32 v[86:87], 0
	v_mov_b64_e32 v[88:89], 0
	v_mov_b64_e32 v[90:91], 0
	v_mov_b64_e32 v[92:93], 0
	v_mov_b64_e32 v[94:95], 0
	v_mov_b64_e32 v[96:97], 0
	v_mov_b64_e32 v[98:99], 0
	v_mov_b64_e32 v[100:101], 0
	v_mov_b64_e32 v[102:103], 0
	v_mov_b64_e32 v[104:105], 0
	v_mov_b64_e32 v[106:107], 0
	v_mov_b64_e32 v[108:109], 0
	v_mov_b64_e32 v[110:111], 0
	v_mov_b64_e32 v[112:113], 0
	v_mov_b64_e32 v[114:115], 0
	v_mov_b64_e32 v[116:117], 0
	v_mov_b64_e32 v[118:119], 0
	v_mov_b64_e32 v[120:121], 0
	v_mov_b64_e32 v[122:123], 0
	v_mov_b64_e32 v[124:125], 0
	v_mov_b64_e32 v[126:127], 0
	v_mov_b64_e32 v[128:129], 0
	s_addc_u32 s5, s27, 0
	s_mov_b32 s37, -2

; template <class Epi, class Sched, bool ALIGN_EPI = false, bool SP2 = false>
; __device__ __forceinline__ void gemm_phase(PG8_LAS unsigned char* lds, const Gemm g, const Sched& S, const Epi& E) {
;     ...
;         const bool has_next = S.next(ui + 1, nxt);
;         const char* nA = has_next ? (const char*)g.A + (size_t)nxt.pm * tstep : cA; const char* nB = has_next ? (const char*)g.Bt + (size_t)nxt.pn * tstep : cB;
;         for (int t = 0; t < nt; t += 2) {
;             const bool last = (t == nt - 2);
;             const char* a1 = cA + (size_t)(t + 1) * kstep;
;             const char* a2 = last ? nA : cA + (size_t)(t + 2) * kstep; const char* b2 = last ? nB : cB + (size_t)(t + 2) * kstep;
;             const char* a3 = a2 + kstep; const char* b3 = b2 + kstep;
;     ...
; #pragma unroll
;         for (int a = 0; a < 2; ++a)
; #pragma unroll
;             for (int b = 0; b < 2; ++b)
; #pragma unroll
;                 for (int m = 0; m < 4; ++m)
; #pragma unroll
;                     for (int n = 0; n < 2; ++n) acc[a][b][m][n] = (f32x4){0.f, 0.f, 0.f, 0.f};
;         cur = nxt; cA = nA; cB = nB; ++ui;
.LBB0_1339:
	s_add_u32 s55, s26, 0x100
	v_mov_b64_e32 v[2:3], 0
	v_mov_b64_e32 v[4:5], 0
	v_mov_b64_e32 v[6:7], 0
	v_mov_b64_e32 v[8:9], 0
	v_mov_b64_e32 v[10:11], 0
	v_mov_b64_e32 v[12:13], 0
	v_mov_b64_e32 v[14:15], 0
	v_mov_b64_e32 v[16:17], 0
	v_mov_b64_e32 v[18:19], 0
	v_mov_b64_e32 v[20:21], 0
	v_mov_b64_e32 v[22:23], 0
	v_mov_b64_e32 v[24:25], 0
	v_mov_b64_e32 v[26:27], 0
	v_mov_b64_e32 v[28:29], 0
	v_mov_b64_e32 v[30:31], 0
	v_mov_b64_e32 v[32:33], 0
	v_mov_b64_e32 v[34:35], 0
	v_mov_b64_e32 v[36:37], 0
	v_mov_b64_e32 v[38:39], 0
	v_mov_b64_e32 v[40:41], 0
	v_mov_b64_e32 v[42:43], 0
	v_mov_b64_e32 v[44:45], 0
	v_mov_b64_e32 v[46:47], 0
	v_mov_b64_e32 v[48:49], 0
	v_mov_b64_e32 v[50:51], 0
	v_mov_b64_e32 v[52:53], 0
	v_mov_b64_e32 v[54:55], 0
	v_mov_b64_e32 v[56:57], 0
	v_mov_b64_e32 v[58:59], 0
	v_mov_b64_e32 v[60:61], 0
	v_mov_b64_e32 v[62:63], 0
	v_mov_b64_e32 v[64:65], 0
	v_mov_b64_e32 v[66:67], 0
	v_mov_b64_e32 v[68:69], 0
	v_mov_b64_e32 v[70:71], 0
	v_mov_b64_e32 v[72:73], 0
	v_mov_b64_e32 v[74:75], 0
	v_mov_b64_e32 v[76:77], 0
	v_mov_b64_e32 v[78:79], 0
	v_mov_b64_e32 v[80:81], 0
	v_mov_b64_e32 v[82:83], 0
	v_mov_b64_e32 v[84:85], 0
	v_mov_b64_e32 v[86:87], 0
	v_mov_b64_e32 v[88:89], 0
	v_mov_b64_e32 v[90:91], 0
	v_mov_b64_e32 v[92:93], 0
	v_mov_b64_e32 v[94:95], 0
	v_mov_b64_e32 v[96:97], 0
	v_mov_b64_e32 v[98:99], 0
	v_mov_b64_e32 v[100:101], 0
	v_mov_b64_e32 v[102:103], 0
	v_mov_b64_e32 v[104:105], 0
	v_mov_b64_e32 v[106:107], 0
	v_mov_b64_e32 v[108:109], 0
	v_mov_b64_e32 v[110:111], 0
	v_mov_b64_e32 v[112:113], 0
	v_mov_b64_e32 v[114:115], 0
	v_mov_b64_e32 v[116:117], 0
	v_mov_b64_e32 v[118:119], 0
	v_mov_b64_e32 v[120:121], 0
	v_mov_b64_e32 v[122:123], 0
	v_mov_b64_e32 v[124:125], 0
	v_mov_b64_e32 v[126:127], 0
	v_mov_b64_e32 v[128:129], 0
	s_addc_u32 s57, s27, 0
	s_mov_b32 s37, -2
